# v26: RWKV pass A serial cumsum: waits after the LDS writes relaxed to lgkmcnt(3) (only the next read is needed), as pass B already has
# speedup vs baseline: 1.0008x; 1.0008x over previous
; template <bool PA> ...
;     ...
;                 const size_t row = cbase + (d ? 63 - j : j);
;                 asm volatile("" ::: "memory");
;                 if (haveT && tlow) tld = *(const u32x4_t*)(tbuf + ((size_t)strm * NCHA + p) * 2304 + tunit * 8);
;                 *(u32x4_t*)(MAT(4) + j * 72 + c8) = *(const u32x4_t*)(HWb + row * 128 + d * 64 + c8);
;                 *(u32x4_t*)(MAT(5) + j * 72 + c8) = *(const u32x4_t*)(HAb + row * 128 + d * 64 + c8);
;                 const u32x4_t rw = *(const u32x4_t*)(Rb + row * 1024 + hc8), kw = *(const u32x4_t*)(Kb + row * 1024 + hc8), vw = *(const u32x4_t*)(Vb + row * 1024 + hc8);
;                 __syncthreads();
;                 { f32x4_t za[2], xa[2]; za[0] = (f32x4_t){0.f, 0.f, 0.f, 0.f}; za[1] = za[0]; xa[0] = za[0]; xa[1] = za[0];
;                   mm2(za, MAT(4), w2T, mt, ntb, r16, kq); mm2(xa, MAT(5), a2T, mt, ntb, r16, kq);
; #pragma unroll
;                   for (int i = 0; i < 2; ++i)
; #pragma unroll
;                       for (int e = 0; e < 4; ++e) { zbuf[(16 * mt + 4 * kq + e) * 64 + 16 * (ntb + i) + r16] = za[i][e]; abuf[(16 * mt + 4 * kq + e) * 64 + 16 * (ntb + i) + r16] = xa[i][e]; } }
;                 __syncthreads();
.LBB0_213:
	s_waitcnt vmcnt(1)
	ds_write_b128 v68, v[232:235] offset:36864
	ds_write_b128 v68, v[236:239] offset:46080
	v_mov_b32_e32 v22, v240
	v_mov_b32_e32 v23, v241
	v_mov_b32_e32 v24, v242
	v_mov_b32_e32 v25, v243
	v_mov_b32_e32 v26, v244
	v_mov_b32_e32 v27, v245
	v_mov_b32_e32 v28, v246
	v_mov_b32_e32 v29, v247
	v_mov_b32_e32 v18, v248
	v_mov_b32_e32 v19, v249
	v_mov_b32_e32 v20, v250
	v_mov_b32_e32 v21, v251
	s_and_b64 s[12:13], s[74:75], exec
	s_cselect_b32 s12, s20, s24
	s_cselect_b32 s13, 64, 0xffffffc0
	v_lshl_add_u32 v226, s12, 6, v160
	s_add_i32 s12, s20, 1
	s_cmp_lt_i32 s12, s21
	s_cselect_b32 s13, s13, 0
	v_add_u32_e32 v226, s13, v226
	v_ashrrev_i32_e32 v227, 31, v226
	v_lshlrev_b64 v[224:225], 8, v[226:227]
	v_lshl_add_u64 v[222:223], v[90:91], 0, v[224:225]
	global_load_dwordx4 v[232:235], v[222:223], off
	v_lshl_add_u64 v[222:223], v[92:93], 0, v[224:225]
	global_load_dwordx4 v[236:239], v[222:223], off
	v_lshlrev_b64 v[224:225], 11, v[226:227]
	v_lshl_add_u64 v[222:223], v[94:95], 0, v[224:225]
	global_load_dwordx4 v[240:243], v[222:223], off
	v_lshl_add_u64 v[222:223], v[96:97], 0, v[224:225]
	global_load_dwordx4 v[244:247], v[222:223], off
	v_lshl_add_u64 v[222:223], v[98:99], 0, v[224:225]
	global_load_dwordx4 v[248:251], v[222:223], off
	s_waitcnt lgkmcnt(0)
	s_barrier
	ds_read_b128 v[186:189], v69 offset:36864
	ds_read_b128 v[190:193], v108
	ds_read_b128 v[204:207], v108 offset:2304
	ds_read_b128 v[208:211], v69 offset:36928
	ds_read_b128 v[212:215], v108 offset:64
	ds_read_b128 v[216:219], v108 offset:2368
	ds_read_b128 v[220:223], v69 offset:46080
	ds_read_b128 v[224:227], v109
	s_nop 0
	s_nop 0
	s_nop 0
	s_waitcnt lgkmcnt(6)
	v_mfma_f32_16x16x32_bf16 v[34:37], v[186:189], v[190:193], 0
	ds_read_b128 v[190:193], v109 offset:2304
	s_nop 0
	v_lshlrev_b32_e32 v161, 16, v26
	s_waitcnt lgkmcnt(6)
	v_mfma_f32_16x16x32_bf16 v[30:33], v[186:189], v[204:207], 0
	ds_read_b128 v[186:189], v69 offset:46144
	ds_read_b128 v[204:207], v109 offset:64
	s_nop 0
	s_nop 0
	v_and_b32_e32 v163, 0xffff0000, v26
	v_lshlrev_b32_e32 v165, 16, v27
	s_waitcnt lgkmcnt(6)
	v_mfma_f32_16x16x32_bf16 v[34:37], v[208:211], v[212:215], v[34:37]
	ds_read_b128 v[212:215], v109 offset:2368
	s_nop 0
	v_and_b32_e32 v167, 0xffff0000, v27
	v_lshlrev_b32_e32 v169, 16, v28
	s_waitcnt lgkmcnt(6)
	v_mfma_f32_16x16x32_bf16 v[30:33], v[208:211], v[216:219], v[30:33]
	s_nop 0
	s_nop 0
	s_nop 0
	v_and_b32_e32 v171, 0xffff0000, v28
	s_waitcnt lgkmcnt(4)
	v_mfma_f32_16x16x32_bf16 v[42:45], v[220:223], v[224:227], 0
	v_lshlrev_b32_e32 v173, 16, v29
	v_and_b32_e32 v175, 0xffff0000, v29
	s_waitcnt lgkmcnt(3)
	v_mfma_f32_16x16x32_bf16 v[38:41], v[220:223], v[190:193], 0
	s_nop 0
	s_nop 0
	s_waitcnt lgkmcnt(1)
	v_mfma_f32_16x16x32_bf16 v[42:45], v[186:189], v[204:207], v[42:45]
	s_nop 0
	s_waitcnt lgkmcnt(0)
	v_mfma_f32_16x16x32_bf16 v[38:41], v[186:189], v[212:215], v[38:41]
	s_nop 4
	ds_write2st64_b32 v144, v34, v42 offset1:64
	ds_write2st64_b32 v145, v35, v43 offset1:64
	ds_write2st64_b32 v148, v36, v44 offset1:64
	ds_write2st64_b32 v149, v37, v45 offset1:64
	ds_write2st64_b32 v150, v30, v38 offset1:64
	ds_write2st64_b32 v151, v31, v39 offset1:64
	ds_write2st64_b32 v152, v32, v40 offset1:64
	ds_write2st64_b32 v153, v33, v41 offset1:64
	s_waitcnt lgkmcnt(0)
	s_barrier
; __device__ __forceinline__ float sigmoidf_(float x) { return __builtin_amdgcn_rcpf(1.0f + __expf(-x)); }
; template <bool PA> ...
;     ...
;                 const unsigned rwa[4] = {rw.x, rw.y, rw.z, rw.w}, kwa[4] = {kw.x, kw.y, kw.z, kw.w};
;                 float kv[8], z[8], aa[8];
; #pragma unroll
;                 for (int q = 0; q < 4; ++q) { rv[2 * q] = __uint_as_float(rwa[q] << 16); rv[2 * q + 1] = __uint_as_float(rwa[q] & 0xffff0000u); kv[2 * q] = __uint_as_float(kwa[q] << 16); kv[2 * q + 1] = __uint_as_float(kwa[q] & 0xffff0000u);
;                 }
;                 vraw = vw;
;                 { const f32x4_t z0 = *(const f32x4_t*)(zbuf + j * 64 + c8), z1 = *(const f32x4_t*)(zbuf + j * 64 + c8 + 4), x0 = *(const f32x4_t*)(abuf + j * 64 + c8), x1 = *(const f32x4_t*)(abuf + j * 64 + c8 + 4);
; #pragma unroll
;                   for (int e = 0; e < 4; ++e) { z[e] = cst[c8 + e] + z0[e]; z[4 + e] = cst[c8 + 4 + e] + z1[e]; aa[e] = cst[64 + c8 + e] + x0[e]; aa[4 + e] = cst[64 + c8 + 4 + e] + x1[e]; } }
;                 asm volatile("" ::: "memory");
;                 float ss = 0.f, bsum = 0.f;
; #pragma unroll
;                 for (int e = 0; e < 8; ++e) { kk[e] = kv[e] * cst[128 + c8 + e]; ss += kk[e] * kk[e]; }
;                 ss += __shfl_xor(ss, 1); ss += __shfl_xor(ss, 2); ss += __shfl_xor(ss, 4);
;                 const float inv = rsqrtf(fmaxf(ss, 1e-24f));
; #pragma unroll
;                 for (int e = 0; e < 8; ++e) { av[e] = sigmoidf_(aa[e]); lw[e] = -0.6065306597f * sigmoidf_(z[e]); kd[e] = kv[e] * (1.0f + (av[e] - 1.0f) * cst[192 + c8 + e]); kk[e] *= inv; bsum += rv[e] * kd[e] * cst[256 + c8 + e]; }
;                 bsum += __shfl_xor(bsum, 1); bsum += __shfl_xor(bsum, 2); bsum += __shfl_xor(bsum, 4);
;                 if (!PA && part == 0) beta[((size_t)d * SLAB + row) * 16 + head] = bsum;
;                 *(f32x4_t*)(cumb + j * 64 + c8) = (f32x4_t){lw[0], lw[1], lw[2], lw[3]}; *(f32x4_t*)(cumb + j * 64 + c8 + 4) = (f32x4_t){lw[4], lw[5], lw[6], lw[7]};
;             }
;             __syncthreads();
;             { const int c = tid & 63, sg = tid >> 6; float run = 0.f;
; #pragma unroll
;               for (int i = 0; i < 8; ++i) { run += cumb[(8 * sg + i) * 64 + c]; cumb[(8 * sg + i) * 64 + c] = run; }
;               segtot[sg * 64 + c] = run; }
	ds_read_b128 v[186:189], v110
	ds_read_b128 v[190:193], v110 offset:16
	ds_read_b128 v[204:207], v111
	ds_read_b128 v[208:211], v111 offset:16
	ds_read_b128 v[212:215], v111 offset:512
	ds_read_b128 v[216:219], v111 offset:528
	s_nop 0
	s_nop 0
	ds_read_b128 v[26:29], v110 offset:16384
	ds_read_b128 v[30:33], v110 offset:16400
	s_nop 0
	s_nop 0
	ds_read_b128 v[34:37], v111 offset:256
	ds_read_b128 v[38:41], v111 offset:272
	s_waitcnt lgkmcnt(2)
	v_add_f32_e32 v42, v186, v204
	s_waitcnt lgkmcnt(2)
	v_add_f32_e32 v50, v190, v208
	v_add_f32_e32 v46, v187, v205
	v_add_f32_e32 v54, v191, v209
	v_add_f32_e32 v49, v188, v206
	v_add_f32_e32 v57, v192, v210
	v_add_f32_e32 v48, v189, v207
	v_add_f32_e32 v56, v193, v211
	s_nop 0
	s_nop 0
	v_and_b32_e32 v45, 64, v198
	v_xor_b32_e32 v44, 1, v198
	v_add_u32_e32 v45, 64, v45
	s_waitcnt lgkmcnt(0)
	v_mul_f32_e32 v164, v213, v163
	v_mul_f32_e32 v162, v212, v161
	v_mul_f32_e32 v43, v164, v164
	v_fmac_f32_e32 v43, v162, v162
	v_mul_f32_e32 v166, v214, v165
	v_fmac_f32_e32 v43, v166, v166
	v_mul_f32_e32 v168, v215, v167
	v_mov_b32_e32 v61, v215
	v_fmac_f32_e32 v43, v168, v168
	s_waitcnt lgkmcnt(0)
	v_mul_f32_e32 v170, v216, v169
	v_fmac_f32_e32 v43, v170, v170
	v_mul_f32_e32 v172, v217, v171
	v_fmac_f32_e32 v43, v172, v172
	v_mul_f32_e32 v174, v218, v173
	v_cmp_lt_i32_e64 s[76:77], v44, v45
	v_fmac_f32_e32 v43, v174, v174
	v_mul_f32_e32 v176, v219, v175
	v_mov_b32_e32 v62, v216
	v_mov_b32_e32 v63, v217
	v_mov_b32_e32 v64, v218
	v_mov_b32_e32 v65, v219
	v_cndmask_b32_e64 v44, v198, v44, s[76:77]
	v_fmac_f32_e32 v43, v176, v176
	v_lshlrev_b32_e32 v44, 2, v44
	ds_bpermute_b32 v44, v44, v43
	v_mul_f32_e32 v42, 0xbfb8aa3b, v42
	v_mul_f32_e32 v46, 0xbfb8aa3b, v46
	v_exp_f32_e32 v42, v42
	v_exp_f32_e32 v46, v46
	v_mul_f32_e32 v50, 0xbfb8aa3b, v50
	v_mul_f32_e32 v54, 0xbfb8aa3b, v54
	s_waitcnt lgkmcnt(0)
	v_add_f32_e32 v43, v43, v44
	v_xor_b32_e32 v44, 2, v198
	v_exp_f32_e32 v50, v50
	v_exp_f32_e32 v54, v54
	v_cmp_lt_i32_e64 s[76:77], v44, v45
	v_mul_f32_e32 v49, 0xbfb8aa3b, v49
	v_mul_f32_e32 v48, 0xbfb8aa3b, v48
	v_cndmask_b32_e64 v44, v198, v44, s[76:77]
	v_lshlrev_b32_e32 v44, 2, v44
	v_add_f32_e32 v42, 1.0, v42
	v_add_f32_e32 v46, 1.0, v46
	v_exp_f32_e32 v49, v49
	v_exp_f32_e32 v48, v48
	v_mul_f32_e32 v57, 0xbfb8aa3b, v57
	v_mul_f32_e32 v56, 0xbfb8aa3b, v56
	ds_bpermute_b32 v44, v44, v43
	v_rcp_f32_e32 v52, v42
	v_rcp_f32_e32 v53, v46
	v_add_f32_e32 v50, 1.0, v50
	v_add_f32_e32 v54, 1.0, v54
	v_exp_f32_e32 v57, v57
	v_exp_f32_e32 v56, v56
	v_rcp_f32_e32 v58, v50
	v_rcp_f32_e32 v59, v54
	v_add_f32_e32 v49, 1.0, v49
	v_add_f32_e32 v48, 1.0, v48
	v_pk_mul_f32 v[46:47], v[52:53], s[30:31] op_sel_hi:[1,0]
	v_rcp_f32_e32 v52, v49
	v_rcp_f32_e32 v53, v48
	v_add_f32_e32 v57, 1.0, v57
	v_add_f32_e32 v56, 1.0, v56
	s_waitcnt lgkmcnt(0)
	v_add_f32_e32 v146, v43, v44
	v_xor_b32_e32 v43, 4, v198
	v_pk_mul_f32 v[54:55], v[58:59], s[30:31] op_sel_hi:[1,0]
	v_rcp_f32_e32 v58, v57
	v_rcp_f32_e32 v59, v56
	v_cmp_lt_i32_e64 s[76:77], v43, v45
	v_pk_mul_f32 v[48:49], v[52:53], s[30:31] op_sel_hi:[1,0]
	ds_read_b128 v[50:53], v111 offset:784
	v_cndmask_b32_e64 v43, v198, v43, s[76:77]
	v_lshlrev_b32_e32 v43, 2, v43
	ds_bpermute_b32 v147, v43, v146
	ds_read_b128 v[42:45], v111 offset:768
	v_pk_mul_f32 v[56:57], v[58:59], s[30:31] op_sel_hi:[1,0]
	ds_write_b128 v112, v[46:49]
	ds_write_b128 v112, v[54:57] offset:16
	s_waitcnt lgkmcnt(0)
	s_barrier
	ds_read2st64_b32 v[186:187], v159 offset1:1
	ds_read2st64_b32 v[188:189], v159 offset0:2 offset1:3
	ds_read2st64_b32 v[190:191], v159 offset0:4 offset1:5
	ds_read2st64_b32 v[192:193], v159 offset0:6 offset1:7
	s_nop 0
	s_waitcnt lgkmcnt(3)
	v_add_f32_e32 v58, 0, v186
	v_add_f32_e32 v60, v58, v187
	ds_write2st64_b32 v159, v58, v60 offset1:1
	s_nop 0
	s_waitcnt lgkmcnt(3)
	v_add_f32_e32 v58, v60, v188
	v_add_f32_e32 v60, v58, v189
	ds_write2st64_b32 v159, v58, v60 offset0:2 offset1:3
	s_nop 0
	s_waitcnt lgkmcnt(3)
	v_add_f32_e32 v58, v60, v190
	v_add_f32_e32 v60, v58, v191
	ds_write2st64_b32 v159, v58, v60 offset0:4 offset1:5
	s_nop 0
	s_waitcnt lgkmcnt(3)
	v_add_f32_e32 v58, v60, v192
	v_add_f32_e32 v59, v58, v193
	ds_write2st64_b32 v159, v58, v59 offset0:6 offset1:7
	ds_write_b32 v113, v59
	v_mov_b32_e32 v58, 0
	s_waitcnt lgkmcnt(0)
	s_barrier
	s_and_saveexec_b64 s[12:13], s[44:45]
	s_cbranch_execz .LBB0_215
	ds_read_b32 v58, v114
	s_waitcnt lgkmcnt(0)
	v_add_f32_e32 v58, 0, v58
